# leader pre-advances its clock by 18 units across its sweep boundary
# baseline (speedup 1.0000x reference)
.Lxp_noswe:
	s_mov_b32 s80, s81
	s_mov_b32 s81, s94
	s_add_i32 s25, s25, 1
	s_cmp_eq_u32 s82, 1
	s_cbranch_scc0 .Lxp_nojump
	s_add_i32 s2, s97, 18560
	s_and_b32 s2, s2, 0x3fff
	v_mov_b32_e32 v245, s2
	s_mov_b64 exec, 1
	global_store_dword v[246:247], v245, off
	s_mov_b64 exec, -1
